# attention loop: drop 22 canonicalising v_max x,x,x that only feed another v_max (exact for non-signalling inputs)
# baseline (speedup 1.0000x reference)
.LBB0_256:
	s_or_b64 exec, exec, s[8:9]
	s_waitcnt vmcnt(0)
	s_waitcnt vmcnt(0) lgkmcnt(0)
	s_barrier
	ds_read_b128 v[48:51], v118
	s_cmp_lg_u32 s90, 0
	s_cselect_b64 s[8:9], -1, 0
	s_sub_i32 s90, s90, 64
	s_add_i32 s91, s91, 0x8000
	s_waitcnt lgkmcnt(0)
	v_max_f32_e32 v50, v50, v51
	v_max3_f32 v48, v48, v49, v50
	v_cmp_ngt_f32_e32 vcc, s86, v48
	s_and_b64 s[8:9], s[8:9], vcc
	s_and_b64 vcc, exec, s[8:9]
	s_cbranch_vccz .LBB0_250

.LBB0_259:
	v_add_u32_e32 v68, s92, v116
	v_add_u32_e32 v70, v68, v120
	ds_read_b128 v[48:51], v70
	ds_read_b128 v[52:55], v70 offset:4096
	ds_read_b128 v[56:59], v70 offset:8192
	ds_read_b128 v[94:97], v70 offset:12288
	v_add_u32_e32 v70, v68, v121
	v_add_u32_e32 v71, v68, v122
	ds_read_b128 v[174:177], v71 offset:12288
	v_add_u32_e32 v68, v68, v123
	ds_read_b128 v[178:181], v68 offset:12288
	s_waitcnt lgkmcnt(0)
	v_mfma_f32_16x16x32_bf16 v[52:55], v[52:55], v[0:3], 0
	v_mfma_f32_16x16x32_bf16 v[98:101], v[56:59], v[0:3], 0
	ds_read_b128 v[56:59], v70 offset:12288
	v_mfma_f32_16x16x32_bf16 v[94:97], v[94:97], v[0:3], 0
	s_waitcnt lgkmcnt(0)
	v_mfma_f32_16x16x32_bf16 v[56:59], v[56:59], v[4:7], v[94:97]
	s_nop 5
	ds_read_b128 v[94:97], v70 offset:8192
	ds_read_b128 v[182:185], v71 offset:8192
	ds_read_b128 v[186:189], v68 offset:8192
	v_mfma_f32_16x16x32_bf16 v[56:59], v[174:177], v[8:11], v[56:59]
	ds_read_b128 v[174:177], v70
	ds_read_b128 v[190:193], v70 offset:4096
	ds_read_b128 v[194:197], v71
	ds_read_b128 v[198:201], v71 offset:4096
	v_mfma_f32_16x16x32_bf16 v[56:59], v[178:181], v[12:15], v[56:59]
	ds_read_b128 v[178:181], v68
	ds_read_b128 v[202:205], v68 offset:4096
	s_waitcnt lgkmcnt(0)
	v_mfma_f32_16x16x32_bf16 v[94:97], v[94:97], v[4:7], v[98:101]
	s_nop 3
	v_exp_f32_e64 v70, -|v56|
	v_exp_f32_e64 v73, -|v57|
	v_mfma_f32_16x16x32_bf16 v[48:51], v[48:51], v[0:3], 0
	v_add_f32_e32 v70, 1.0, v70
	v_log_f32_e32 v70, v70
	v_max_f32_e32 v68, 0, v56
	v_mfma_f32_16x16x32_bf16 v[94:97], v[182:185], v[8:11], v[94:97]
	v_add_f32_e32 v68, v68, v70
	v_mfma_f32_16x16x32_bf16 v[52:55], v[190:193], v[4:7], v[52:55]
	v_max_f32_e32 v71, 0, v57
	v_add_f32_e32 v70, 1.0, v73
	v_mfma_f32_16x16x32_bf16 v[48:51], v[174:177], v[4:7], v[48:51]
	v_max_f32_e32 v193, 0, v58
	v_max_f32_e32 v183, 0, v59
	v_mfma_f32_16x16x32_bf16 v[174:177], v[186:189], v[12:15], v[94:97]
	v_log_f32_e32 v191, v70
	v_exp_f32_e64 v70, -|v58|
	v_mfma_f32_16x16x32_bf16 v[52:55], v[198:201], v[8:11], v[52:55]
	v_add_u32_e32 v198, s90, v159
	s_nop 3
	v_exp_f32_e64 v73, -|v174|
	v_exp_f32_e64 v94, -|v175|
	v_mfma_f32_16x16x32_bf16 v[52:55], v[202:205], v[12:15], v[52:55]
	v_exp_f32_e64 v96, -|v177|
	v_add_f32_e32 v73, 1.0, v73
	v_log_f32_e32 v190, v73
	v_max_f32_e32 v192, 0, v175
	v_add_f32_e32 v73, 1.0, v94
	v_exp_f32_e64 v94, -|v176|
	s_nop 0
	s_nop 0
	v_exp_f32_e64 v97, -|v52|
	v_add_f32_e32 v96, 1.0, v96
	v_mfma_f32_16x16x32_bf16 v[48:51], v[194:197], v[8:11], v[48:51]
	v_log_f32_e32 v194, v73
	v_log_f32_e32 v96, v96
	v_max_f32_e32 v182, 0, v176
	v_add_f32_e32 v73, 1.0, v94
	v_add_f32_e32 v97, 1.0, v97
	v_log_f32_e32 v94, v73
	v_log_f32_e32 v97, v97
	v_max_f32_e32 v73, 0, v177
	v_add_f32_e32 v185, v73, v96
	v_exp_f32_e64 v96, -|v54|
	v_max_f32_e32 v73, 0, v52
	v_add_f32_e32 v97, v73, v97
	v_exp_f32_e64 v73, -|v53|
	v_add_f32_e32 v96, 1.0, v96
	v_mfma_f32_16x16x32_bf16 v[48:51], v[178:181], v[12:15], v[48:51]
	v_log_f32_e32 v96, v96
	v_add_f32_e32 v73, 1.0, v73
	v_log_f32_e32 v181, v73
	v_max_f32_e32 v73, 0, v54
	v_add_f32_e32 v196, v73, v96
	s_nop 1
	s_nop 0
	v_exp_f32_e64 v96, -|v48|
	v_exp_f32_e64 v73, -|v55|
	v_exp_f32_e64 v100, -|v50|
	v_add_f32_e32 v70, 1.0, v70
	v_add_f32_e32 v96, 1.0, v96
	v_log_f32_e32 v96, v96
	v_add_f32_e32 v73, 1.0, v73
	v_log_f32_e32 v180, v73
	v_max_f32_e32 v73, 0, v48
	v_add_f32_e32 v73, v73, v96
	v_exp_f32_e64 v96, -|v49|
	v_log_f32_e32 v195, v70
	v_exp_f32_e64 v70, -|v59|
	v_add_f32_e32 v96, 1.0, v96
	v_log_f32_e32 v101, v96
	v_add_f32_e32 v96, 1.0, v100
	v_max_f32_e32 v179, 0, v53
	v_log_f32_e32 v96, v96
	v_max_f32_e32 v178, 0, v55
	v_exp_f32_e64 v100, -|v51|
	v_max_f32_e32 v99, 0, v49
	v_max_f32_e32 v98, 0, v50
	v_add_f32_e32 v70, 1.0, v70
	v_add_f32_e32 v197, v98, v96
	v_log_f32_e32 v95, v70
	v_max_f32_e32 v98, 0, v51
	v_add_f32_e32 v96, 1.0, v100
	v_cmp_lt_u32_e64 s[12:13], v198, v60
	v_log_f32_e32 v100, v96
	s_nop 0
	v_cndmask_b32_e64 v96, 0, -v73, s[12:13]
	v_or_b32_e32 v73, 48, v198
	v_max_f32_e32 v70, 0, v174
	v_or_b32_e32 v188, 33, v198
	v_or_b32_e32 v189, 32, v198
	v_or_b32_e32 v201, 49, v198
	v_cmp_lt_u32_e64 s[14:15], v73, v60
	v_or_b32_e32 v204, 50, v198
	v_pk_add_f32 v[70:71], v[70:71], v[190:191]
	v_cndmask_b32_e64 v184, 0, -v68, s[14:15]
	v_pk_add_f32 v[186:187], v[192:193], v[194:195]
	v_cmp_lt_u32_e64 s[16:17], v204, v60
	v_cmp_lt_u32_e32 vcc, v188, v61
	v_cmp_lt_u32_e64 s[18:19], v201, v61
	v_cmp_lt_u32_e64 s[8:9], v189, v60
	v_add_f32_e32 v73, 0, v184
	v_or_b32_e32 v202, 34, v198
	v_or_b32_e32 v203, 51, v198
	v_pk_add_f32 v[94:95], v[182:183], v[94:95]
	v_cndmask_b32_e64 v183, 0, -v187, s[16:17]
	v_cndmask_b32_e64 v182, 0, -v186, vcc
	v_cndmask_b32_e64 v187, 0, -v71, s[18:19]
	v_cndmask_b32_e64 v186, 0, -v70, s[8:9]
	v_pk_add_f32 v[70:71], v[186:187], v[72:73]
	v_cmp_lt_u32_e64 s[24:25], v203, v61
	v_cmp_lt_u32_e64 s[20:21], v202, v60
	v_pk_add_f32 v[70:71], v[182:183], v[70:71]
	v_cndmask_b32_e64 v189, 0, -v95, s[24:25]
	v_cndmask_b32_e64 v188, 0, -v94, s[20:21]
	v_pk_add_f32 v[70:71], v[188:189], v[70:71]
	ds_bpermute_b32 v95, v85, v71
	v_or_b32_e32 v68, 35, v198
	v_cmp_lt_u32_e64 s[10:11], v68, v61
	ds_bpermute_b32 v191, v87, v71
	v_add_f32_e32 v201, v176, v188
	v_cndmask_b32_e64 v94, 0, -v185, s[10:11]
	s_waitcnt lgkmcnt(0)
	v_pk_add_f32 v[70:71], v[94:95], v[70:71]
	ds_bpermute_b32 v190, v85, v70
	ds_bpermute_b32 v193, v87, v95
	ds_bpermute_b32 v192, v87, v70
	v_add_f32_e32 v185, v58, v183
	v_cndmask_b32_e64 v58, 0, v95, s[0:1]
	s_waitcnt lgkmcnt(0)
	ds_bpermute_b32 v68, v87, v190
	v_pk_add_f32 v[70:71], v[70:71], v[190:191]
	v_cndmask_b32_e64 v73, 0, v190, s[0:1]
	v_cndmask_b32_e64 v95, 0, v192, s[22:23]
	v_pk_add_f32 v[70:71], v[70:71], v[192:193]
	v_add_f32_e32 v73, v73, v95
	s_waitcnt lgkmcnt(0)
	v_cndmask_b32_e64 v95, 0, v68, s[4:5]
	v_pk_add_f32 v[194:195], v[70:71], v[68:69]
	v_cndmask_b32_e64 v68, 0, v191, s[22:23]
	v_add_f32_e32 v58, v58, v68
	v_cndmask_b32_e64 v68, 0, v193, s[4:5]
	v_mov_b32_e32 v70, v188
	v_add_f32_e32 v188, v58, v68
	v_mov_b32_e32 v58, v69
	v_pk_add_f32 v[58:59], v[58:59], v[188:189]
	v_add_f32_e32 v202, v177, v94
	v_pk_add_f32 v[176:177], v[72:73], v[94:95]
	v_mov_b32_e32 v71, v195
	v_add_f32_e32 v68, v58, v59
	v_pk_add_f32 v[70:71], v[70:71], v[176:177]
	v_add_f32_e32 v68, 0, v68
	v_add_f32_e32 v204, v175, v182
	v_mov_b32_e32 v94, v182
	v_mov_b32_e32 v95, v174
	v_mov_b32_e32 v174, v70
	v_mov_b32_e32 v175, v186
	v_exp_f32_e32 v177, v68
	v_mov_b32_e32 v68, v189
	v_mov_b32_e32 v69, v57
	v_mov_b32_e32 v73, v187
	v_pk_add_f32 v[94:95], v[94:95], v[174:175]
	v_pk_add_f32 v[68:69], v[68:69], v[72:73]
	v_pk_mov_b32 v[174:175], v[182:183], v[58:59] op_sel:[1,0]
	v_add_f32_e32 v186, v58, v185
	v_pk_add_f32 v[174:175], v[174:175], v[68:69]
	v_mov_b32_e32 v57, v187
	v_mov_b32_e32 v185, v174
	v_pk_add_f32 v[56:57], v[56:57], v[184:185]
	v_add_f32_e32 v59, v68, v186
	v_add_f32_e32 v56, v58, v56
	v_add_f32_e32 v56, v56, v57
	v_exp_f32_e32 v56, v56
	v_exp_f32_e32 v59, v59
	v_add_f32_e32 v68, v174, v175
	v_exp_f32_e32 v68, v68
	v_cndmask_b32_e64 v187, 0, v56, s[14:15]
	v_add_f32_e32 v56, v201, v71
	v_add_f32_e32 v56, v176, v56
	v_exp_f32_e32 v56, v56
	v_add_f32_e32 v57, v202, v71
	v_add_f32_e32 v57, 0, v57
	v_or_b32_e32 v58, 2, v198
	v_cndmask_b32_e64 v189, 0, v56, s[20:21]
	v_or_b32_e32 v56, 16, v198
	v_cndmask_b32_e64 v185, 0, v59, s[16:17]
	v_exp_f32_e32 v188, v57
	v_or_b32_e32 v57, 17, v198
	v_cmp_lt_u32_e64 s[16:17], v56, v60
	v_cmp_lt_u32_e64 s[14:15], v58, v60
	v_cndmask_b32_e64 v186, 0, v68, s[18:19]
	v_cndmask_b32_e64 v56, 0, -v97, s[16:17]
	v_cndmask_b32_e64 v58, 0, -v197, s[14:15]
	v_or_b32_e32 v68, 18, v198
	v_pk_add_f32 v[174:175], v[178:179], v[180:181]
	v_cmp_lt_u32_e64 s[20:21], v57, v61
	v_add_f32_e32 v59, 0, v56
	v_add_f32_e32 v191, v50, v58
	v_or_b32_e32 v50, 19, v198
	v_cmp_lt_u32_e64 s[18:19], v68, v60
	v_cndmask_b32_e64 v175, 0, -v175, s[20:21]
	v_cndmask_b32_e64 v184, 0, v177, s[24:25]
	v_cndmask_b32_e64 v68, 0, -v196, s[18:19]
	v_cmp_lt_u32_e64 s[24:25], v50, v61
	v_add_f32_e32 v50, v175, v59
	v_add_f32_e32 v50, v68, v50
	v_cndmask_b32_e64 v174, 0, -v174, s[24:25]
	v_add_f32_e32 v50, v174, v50
	ds_bpermute_b32 v57, v85, v50
	ds_bpermute_b32 v176, v87, v50
	v_mov_b32_e32 v73, v53
	v_mov_b32_e32 v181, v194
	v_mov_b32_e32 v183, v195
	s_waitcnt lgkmcnt(0)
	ds_bpermute_b32 v177, v87, v57
	v_add_f32_e32 v50, v50, v57
	v_add_f32_e32 v179, v50, v176
	v_cndmask_b32_e64 v50, 0, v57, s[0:1]
	v_cndmask_b32_e64 v53, 0, v176, s[22:23]
	v_add_f32_e32 v180, v50, v53
	s_waitcnt lgkmcnt(0)
	v_cndmask_b32_e64 v182, 0, v177, s[4:5]
	v_pk_add_f32 v[180:181], v[180:181], v[182:183]
	v_add_f32_e32 v69, v54, v68
	v_mov_b32_e32 v53, v180
	v_mov_b32_e32 v57, v181
	v_add_f32_e32 v59, v55, v174
	v_pk_add_f32 v[52:53], v[52:53], v[56:57]
	v_pk_add_f32 v[54:55], v[72:73], v[174:175]
	v_add_f32_e32 v50, v59, v53
	v_add_f32_e32 v56, v69, v53
	v_add_f32_e32 v50, 0, v50
	v_add_f32_e32 v56, v54, v56
	v_exp_f32_e32 v56, v56
	v_exp_f32_e32 v50, v50
	v_mov_b32_e32 v69, v53
	v_add_u32_e32 v199, 1, v198
	v_pk_add_f32 v[54:55], v[68:69], v[54:55]
	v_or_b32_e32 v97, 3, v198
	v_cndmask_b32_e64 v68, 0, v56, s[18:19]
	v_cndmask_b32_e64 v69, 0, v50, s[24:25]
	v_add_f32_e32 v50, v54, v55
	v_add_f32_e32 v55, v52, v53
	v_pk_add_f32 v[52:53], v[98:99], v[100:101]
	v_cmp_lt_u32_e64 s[18:19], v199, v61
	v_add_f32_e32 v200, 0, v96
	v_cmp_lt_u32_e64 s[24:25], v97, v61
	v_cndmask_b32_e64 v57, 0, -v53, s[18:19]
	v_exp_f32_e32 v50, v50
	v_cndmask_b32_e64 v56, 0, -v52, s[24:25]
	v_add_f32_e32 v52, v57, v200
	v_add_f32_e32 v52, v58, v52
	v_add_f32_e32 v182, v56, v52
	ds_bpermute_b32 v183, v85, v182
	v_add_f32_e32 v52, v175, v54
	ds_bpermute_b32 v192, v87, v182
	v_add_f32_e32 v52, v52, v55
	v_exp_f32_e32 v52, v52
	s_waitcnt lgkmcnt(0)
	ds_bpermute_b32 v193, v87, v183
	v_cndmask_b32_e64 v178, 0, v183, s[0:1]
	v_cndmask_b32_e64 v176, 0, v192, s[22:23]
	v_cndmask_b32_e64 v99, 0, v52, s[16:17]
	v_pk_add_f32 v[52:53], v[178:179], v[176:177]
	s_waitcnt lgkmcnt(0)
	v_cndmask_b32_e64 v180, 0, v193, s[4:5]
	v_pk_add_f32 v[52:53], v[52:53], v[180:181]
	v_mov_b32_e32 v73, v49
	v_mov_b32_e32 v49, v52
	v_mov_b32_e32 v97, v53
	v_pk_add_f32 v[48:49], v[48:49], v[96:97]
	v_cndmask_b32_e64 v98, 0, v50, s[20:21]
	v_add_f32_e32 v100, v51, v56
	v_pk_add_f32 v[50:51], v[72:73], v[56:57]
	v_mov_b32_e32 v59, v49
	v_pk_add_f32 v[54:55], v[58:59], v[50:51]
	v_add_f32_e32 v51, v100, v49
	v_add_f32_e32 v52, v191, v49
	v_add_f32_e32 v48, v48, v49
	v_add_f32_e32 v49, v57, v54
	v_add_f32_e32 v51, 0, v51
	v_add_f32_e32 v50, v50, v52
	v_add_f32_e32 v52, v54, v55
	v_add_f32_e32 v48, v49, v48
	v_exp_f32_e32 v51, v51
	v_exp_f32_e32 v50, v50
	v_exp_f32_e32 v52, v52
	v_exp_f32_e32 v48, v48
	v_bfe_u32 v59, v68, 16, 1
	v_cndmask_b32_e64 v49, 0, v50, s[14:15]
	v_cndmask_b32_e64 v50, 0, v51, s[24:25]
	v_cndmask_b32_e64 v51, 0, v52, s[18:19]
	v_cndmask_b32_e64 v48, 0, v48, s[12:13]
	v_add_u32_e32 v52, s92, v75
	v_bfe_u32 v56, v48, 16, 1
	v_bfe_u32 v57, v51, 16, 1
	v_bfe_u32 v73, v50, 16, 1
	v_bfe_u32 v96, v49, 16, 1
	v_add3_u32 v59, v68, v59, s84
	v_add3_u32 v68, v52, v124, v117
	v_add3_u32 v191, v52, v125, v117
	v_add3_u32 v97, v51, v57, s84
	v_add3_u32 v100, v48, v56, s84
	v_add3_u32 v101, v49, v96, s84
	v_add3_u32 v73, v50, v73, s84
	ds_read2st64_b64 v[48:51], v68 offset0:32 offset1:36
	ds_read2st64_b64 v[54:57], v191 offset0:32 offset1:36
	v_bfe_u32 v58, v69, 16, 1
	v_add3_u32 v58, v69, v58, s84
	v_cvt_pk_bf16_f32 v98, v99, v98
	s_waitcnt lgkmcnt(0)
	v_mov_b32_e32 v174, v48
	v_mov_b32_e32 v175, v49
	v_mov_b32_e32 v176, v54
	v_mov_b32_e32 v177, v55
	v_perm_b32 v96, v97, v100, s85
	v_perm_b32 v99, v58, v59, s85
	v_perm_b32 v97, v73, v101, s85
	ds_read2st64_b64 v[178:181], v68 offset0:40 offset1:44
	v_mov_b32_e32 v54, v50
	v_mfma_f32_16x16x32_bf16 v[16:19], v[174:177], v[96:99], v[16:19]
	ds_read2st64_b64 v[174:177], v191 offset0:40 offset1:44
	v_mov_b32_e32 v55, v51
	s_waitcnt lgkmcnt(0)
	v_mov_b32_e32 v48, v178
	v_mov_b32_e32 v49, v179
	v_add_f32_e32 v190, v204, v71
	v_mov_b32_e32 v50, v174
	v_mov_b32_e32 v51, v175
	v_mfma_f32_16x16x32_bf16 v[20:23], v[54:57], v[96:99], v[20:23]
	v_add_f32_e32 v54, v70, v190
	v_exp_f32_e32 v58, v54
	ds_read2st64_b64 v[54:57], v68 offset0:48 offset1:52
	v_mfma_f32_16x16x32_bf16 v[24:27], v[48:51], v[96:99], v[24:27]
	ds_read2st64_b64 v[48:51], v191 offset0:48 offset1:52
	v_mov_b32_e32 v174, v180
	v_mov_b32_e32 v175, v181
	s_waitcnt lgkmcnt(0)
	v_mov_b32_e32 v178, v54
	v_mov_b32_e32 v179, v55
	v_mov_b32_e32 v180, v48
	v_add_f32_e32 v48, v95, v71
	v_mov_b32_e32 v181, v49
	v_mfma_f32_16x16x32_bf16 v[32:35], v[174:177], v[96:99], v[32:35]
	v_add_f32_e32 v59, v94, v48
	ds_read2st64_b64 v[68:71], v68 offset0:56 offset1:60
	ds_read2st64_b64 v[174:177], v191 offset0:56 offset1:60
	v_mov_b32_e32 v48, v56
	v_mov_b32_e32 v49, v57
	v_mfma_f32_16x16x32_bf16 v[28:31], v[178:181], v[96:99], v[28:31]
	s_waitcnt lgkmcnt(0)
	v_mov_b32_e32 v54, v68
	v_mov_b32_e32 v55, v69
	v_mov_b32_e32 v56, v174
	v_mov_b32_e32 v57, v175
	v_mfma_f32_16x16x32_bf16 v[36:39], v[48:51], v[96:99], v[36:39]
	v_exp_f32_e32 v48, v59
	v_mov_b32_e32 v174, v70
	v_mov_b32_e32 v175, v71
	v_cndmask_b32_e64 v49, 0, v188, s[10:11]
	v_cndmask_b32_e32 v50, 0, v58, vcc
	v_cndmask_b32_e64 v48, 0, v48, s[8:9]
	v_mfma_f32_16x16x32_bf16 v[40:43], v[54:57], v[96:99], v[40:43]
	v_bfe_u32 v51, v48, 16, 1
	v_bfe_u32 v54, v50, 16, 1
	v_bfe_u32 v55, v49, 16, 1
	v_mfma_f32_16x16x32_bf16 v[44:47], v[174:177], v[96:99], v[44:47]
	v_bfe_u32 v56, v189, 16, 1
	v_add3_u32 v174, v52, v126, v117
	v_add3_u32 v52, v52, v127, v117
	v_add3_u32 v69, v50, v54, s84
	v_add3_u32 v70, v48, v51, s84
	v_add3_u32 v73, v189, v56, s84
	v_add3_u32 v95, v49, v55, s84
	ds_read2st64_b64 v[48:51], v174 offset0:32 offset1:36
	ds_read2st64_b64 v[54:57], v52 offset0:32 offset1:36
	v_perm_b32 v94, v69, v70, s85
	s_waitcnt lgkmcnt(0)
	v_mov_b32_e32 v68, v48
	v_mov_b32_e32 v69, v49
	v_mov_b32_e32 v70, v54
	v_mov_b32_e32 v71, v55
	v_perm_b32 v95, v95, v73, s85
	v_cvt_pk_bf16_f32 v96, v187, v186
	v_cvt_pk_bf16_f32 v97, v185, v184
	ds_read2st64_b64 v[98:101], v174 offset0:40 offset1:44
	v_mov_b32_e32 v54, v50
	v_mfma_f32_16x16x32_bf16 v[16:19], v[68:71], v[94:97], v[16:19]
	ds_read2st64_b64 v[68:71], v52 offset0:40 offset1:44
	v_mov_b32_e32 v55, v51
	s_waitcnt lgkmcnt(0)
	v_mov_b32_e32 v48, v98
	v_mov_b32_e32 v49, v99
	v_mfma_f32_16x16x32_bf16 v[20:23], v[54:57], v[94:97], v[20:23]
	v_mov_b32_e32 v50, v68
	v_mov_b32_e32 v51, v69
	v_add_f32_e32 v54, v182, v183
	v_add_f32_e32 v58, v54, v192
	ds_read2st64_b64 v[54:57], v174 offset0:48 offset1:52
	v_mov_b32_e32 v68, v100
	v_mov_b32_e32 v69, v101
	v_mfma_f32_16x16x32_bf16 v[24:27], v[48:51], v[94:97], v[24:27]
	ds_read2st64_b64 v[48:51], v52 offset0:48 offset1:52
	s_waitcnt lgkmcnt(0)
	v_mov_b32_e32 v98, v54
	v_add_f32_e32 v54, v58, v193
	v_mfma_f32_16x16x32_bf16 v[32:35], v[68:71], v[94:97], v[32:35]
	v_add_f32_e32 v69, v54, v53
	v_mov_b32_e32 v100, v48
	v_mov_b32_e32 v48, v56
	v_mov_b32_dpp v56, v69 quad_perm:[1,0,3,2] row_mask:0xf bank_mask:0xf
	v_mov_b32_e32 v101, v49
	v_mov_b32_e32 v49, v57
	v_mov_b32_e32 v99, v55
	s_waitcnt lgkmcnt(0)
	v_max_f32_e32 v68, v69, v56
	s_nop 1
	v_mov_b32_dpp v70, v68 quad_perm:[2,3,0,1] row_mask:0xf bank_mask:0xf
	v_mfma_f32_16x16x32_bf16 v[36:39], v[48:51], v[94:97], v[36:39]
	ds_read2st64_b64 v[48:51], v174 offset0:56 offset1:60
	ds_read2st64_b64 v[52:55], v52 offset0:56 offset1:60
	s_waitcnt lgkmcnt(0)
	v_mov_b32_e32 v56, v48
	v_max_f32_e32 v48, v68, v70
	v_mov_b32_e32 v57, v49
	s_nop 0
	v_mov_b32_dpp v49, v48 row_half_mirror row_mask:0xf bank_mask:0xf
	v_mov_b32_e32 v58, v52
	v_mov_b32_e32 v59, v53
	v_mov_b32_e32 v52, v50
	v_mov_b32_e32 v53, v51
	s_waitcnt lgkmcnt(0)
	v_max_f32_e32 v49, v49, v49
	v_max_f32_e32 v48, v48, v49
	s_nop 1
	v_mov_b32_dpp v49, v48 row_mirror row_mask:0xf bank_mask:0xf
	v_mfma_f32_16x16x32_bf16 v[28:31], v[98:101], v[94:97], v[28:31]
	v_mfma_f32_16x16x32_bf16 v[40:43], v[56:59], v[94:97], v[40:43]
	v_mfma_f32_16x16x32_bf16 v[44:47], v[52:55], v[94:97], v[44:47]
	s_and_saveexec_b64 s[8:9], s[6:7]
	s_cbranch_execz .LBB0_256
	s_waitcnt lgkmcnt(0)
	v_max_f32_e32 v48, v48, v49
	ds_write_b32 v119, v48
	s_branch .LBB0_256
